# EpiRes (FFN down GEMM): residual loads of the second row half issued together with the first half (into free fragment registers), one vmcnt wait instead of two exposed latencies
# baseline (speedup 1.0000x reference)
; #define LAS __attribute__((address_space(3)))
; __device__ __forceinline__ void gla_scan_phase2(LAS unsigned char* lds, const bf16_t* proj, const float* gbuf, const float* wgu  , const float* bg  ,
;                                                 bf16_t* ob0, bf16_t* ob1) {
;     ...
;             bf16x8 wbh, wbl;
;             {
;                 unsigned hi_[4], lo_[4];
; #pragma unroll
;                 for (int q = 0; q < 4; ++q) {
;                     const float w0 = wgu[(size_t)(dir * 16 + 8 * hh + 2 * q) * 512 + h * 128 + 32 * zd + r], w1 = wgu[(size_t)(dir * 16 + 8 * hh + 2 * q + 1) * 512 + h * 128 + 32 * zd + r];
;                     hi_[q] = pk2(w0, w1); lo_[q] = pk2(w0 - bflo(hi_[q]), w1 - bfhi(hi_[q]));
;                 }
;                 wbh = __builtin_bit_cast(bf16x8, (u32x4){hi_[0], hi_[1], hi_[2], hi_[3]}); wbl = __builtin_bit_cast(bf16x8, (u32x4){lo_[0], lo_[1], lo_[2], lo_[3]});
;             }
;             const float zbias = bg[dir * 512 + h * 128 + 32 * zd + r];
;             const __amdgpu_buffer_rsrc_t prs = __builtin_amdgcn_make_buffer_rsrc((void*)proj, 0, (unsigned)((size_t)MTOK * GINP * 2), 0x00020000);
;             const unsigned qvoff = (unsigned)((16 * seg * GINP + h * 128 + d) * 2), vvoff = (unsigned)((16 * seg * GINP + 1024 + h * 256 + 2 * d) * 2);
;             f32x4 gna, gnb;
;             { const float* grow = gbuf + (size_t)(b * SEQ + (dir ? NCH - 1 : 0) * CH + r) * 32 + dir * 16 + 8 * hh; gna = *(const f32x4*)grow; gnb = *(const f32x4*)(grow + 4); }
;             for (int n = 0; n <= NCH; ++n) {
;                 if (n < NCH) {
;                     const int tok0 = b * SEQ + (dir ? NCH - 1 - n : n) * CH;
;                     LAS unsigned char* set = lds + (n & 1) * G2_SET;
;                     const f32x4 ga = gna, gb = gnb;
;                     const unsigned srow = (unsigned)tok0 * (unsigned)(GINP * 2);
;                     unsigned short qv[16], kv[16];
; #pragma unroll
;                     for (int ii = 0; ii < 16; ++ii) { qv[ii] = __builtin_amdgcn_raw_buffer_load_b16(prs, qvoff, srow + (unsigned)(ii * GINP * 2), 0);
;                                                        kv[ii] = __builtin_amdgcn_raw_buffer_load_b16(prs, qvoff + 1024u, srow + (unsigned)(ii * GINP * 2), 0); }
;                     unsigned vw[16];
; #pragma unroll
.LBB0_217:
	s_and_b64 vcc, exec, s[6:7]
	s_cbranch_vccz .LBB0_212
	s_nop 7
	v_lshl_or_b32 v0, s8, 13, v198
	s_lshl_b32 s0, s15, 7
	v_or_b32_e32 v0, s0, v0
	v_lshlrev_b32_e32 v160, 2, v0
	v_lshl_add_u64 v[0:1], s[16:17], 0, v[160:161]
	v_lshl_add_u64 v[0:1], s[22:23], 2, v[0:1]
	v_mov_b32_e32 v193, v161
	v_lshl_add_u64 v[0:1], v[0:1], 0, v[192:193]
	global_load_dword v2, v[0:1], off
	global_load_dword v3, v[0:1], off offset:2048
	s_movk_i32 s6, 0x1000
	s_lshl_b32 s9, s9, 11
	v_lshlrev_b32_e32 v160, 2, v188
	s_mov_b32 s20, 0
	v_or_b32_e32 v52, s9, v186
	s_waitcnt vmcnt(0)
	v_cvt_pk_bf16_f32 v32, v2, v3
	v_lshlrev_b32_e32 v4, 16, v32
	v_and_b32_e32 v5, 0xffff0000, v32
	v_pk_add_f32 v[2:3], v[2:3], v[4:5] neg_lo:[0,1] neg_hi:[0,1]
	s_nop 0
	v_cvt_pk_bf16_f32 v36, v2, v3
	v_add_co_u32_e32 v2, vcc, s6, v0
	s_movk_i32 s6, 0x2000
	s_nop 0
	v_addc_co_u32_e32 v3, vcc, 0, v1, vcc
	v_add_co_u32_e32 v4, vcc, s6, v0
	s_movk_i32 s6, 0x3000
	s_nop 0
	v_addc_co_u32_e32 v5, vcc, 0, v1, vcc
	global_load_dword v6, v[4:5], off offset:-4096
	global_load_dword v7, v[2:3], off offset:2048
	v_add_co_u32_e32 v0, vcc, s6, v0
	s_lshl_b32 s6, s8, 9
	s_nop 0
	v_addc_co_u32_e32 v1, vcc, 0, v1, vcc
	s_or_b32 s6, s0, s6
	s_cmp_lg_u32 s8, 0
	s_cselect_b64 s[68:69], -1, 0
	s_cmp_eq_u32 s8, 0
	s_cselect_b64 s[48:49], -1, 0
	s_waitcnt vmcnt(0)
	v_cvt_pk_bf16_f32 v33, v6, v7
	v_lshlrev_b32_e32 v2, 16, v33
	v_and_b32_e32 v3, 0xffff0000, v33
	v_pk_add_f32 v[2:3], v[6:7], v[2:3] neg_lo:[0,1] neg_hi:[0,1]
	s_nop 0
	v_cvt_pk_bf16_f32 v37, v2, v3
	global_load_dword v2, v[4:5], off
	global_load_dword v3, v[4:5], off offset:2048
	s_waitcnt vmcnt(0)
	v_cvt_pk_bf16_f32 v34, v2, v3
	v_lshlrev_b32_e32 v4, 16, v34
	v_and_b32_e32 v5, 0xffff0000, v34
	v_pk_add_f32 v[2:3], v[2:3], v[4:5] neg_lo:[0,1] neg_hi:[0,1]
	s_nop 0
	v_cvt_pk_bf16_f32 v38, v2, v3
	global_load_dword v2, v[0:1], off
	global_load_dword v3, v[0:1], off offset:2048
	s_waitcnt vmcnt(0)
	v_cvt_pk_bf16_f32 v35, v2, v3
	v_lshlrev_b32_e32 v0, 16, v35
	v_and_b32_e32 v1, 0xffff0000, v35
	v_pk_add_f32 v[0:1], v[2:3], v[0:1] neg_lo:[0,1] neg_hi:[0,1]
	s_nop 0
	v_cvt_pk_bf16_f32 v39, v0, v1
	v_add_u32_e32 v0, s6, v199
	v_ashrrev_i32_e32 v1, 31, v0
	v_lshl_add_u64 v[0:1], v[0:1], 2, s[18:19]
	global_load_dword v0, v[0:1], off
	v_or_b32_e32 v1, s0, v200
	s_and_b64 s[6:7], s[48:49], exec
	v_lshlrev_b32_e32 v50, 1, v1
	v_lshl_or_b32 v1, s15, 9, v213
	s_cselect_b32 s0, 0, 0x7e0
	v_or_b32_e32 v51, 0x800, v1
	v_or_b32_e32 v1, s0, v186
	v_or_b32_e32 v2, s9, v1
	v_ashrrev_i32_e32 v3, 31, v2
	v_readlane_b32 s6, v253, 19
	v_lshlrev_b64 v[2:3], 7, v[2:3]
	v_readlane_b32 s7, v253, 20
	s_lshl_b32 s28, s8, 6
	v_lshl_add_u64 v[48:49], v[190:191], 0, s[28:29]
	v_lshl_add_u64 v[2:3], s[6:7], 0, v[2:3]
	v_lshl_add_u64 v[2:3], v[2:3], 0, s[28:29]
	v_lshl_add_u64 v[2:3], v[2:3], 0, v[160:161]
	global_load_dwordx4 v[40:43], v[2:3], off offset:16
	global_load_dwordx4 v[44:47], v[2:3], off
	v_or_b32_e32 v53, 0x400, v50
	s_xor_b64 s[50:51], s[40:41], s[48:49]
	s_xor_b64 s[52:53], s[42:43], s[48:49]
	s_xor_b64 s[54:55], s[44:45], s[48:49]
	s_xor_b64 s[56:57], s[46:47], s[48:49]
	s_mov_b32 s8, 63
	s_waitcnt vmcnt(2)
	v_mov_b32_e32 v1, v0
	v_mov_b32_e32 v2, v0
	v_mov_b32_e32 v3, v0
	v_mov_b32_e32 v4, v0
	v_mov_b32_e32 v5, v0
	v_mov_b32_e32 v6, v0
	v_mov_b32_e32 v7, v0
	v_mov_b32_e32 v8, v0
	v_mov_b32_e32 v9, v0
	v_mov_b32_e32 v10, v0
	v_mov_b32_e32 v11, v0
	v_mov_b32_e32 v12, v0
	v_mov_b32_e32 v13, v0
	v_mov_b32_e32 v14, v0
	v_mov_b32_e32 v15, v0
	s_branch .LBB0_220
.LBB0_219:
	s_or_b64 exec, exec, s[6:7]
	s_waitcnt vmcnt(17)
	v_lshrrev_b32_e32 v17, 16, v68
	s_waitcnt vmcnt(15)
	v_lshrrev_b32_e32 v18, 16, v66
	s_waitcnt vmcnt(13)
	v_lshrrev_b32_e32 v19, 16, v64
	v_and_b32_e32 v16, 0xffff, v68
	v_and_or_b32 v20, v69, s77, v17
	v_and_b32_e32 v17, 0xffff, v66
	v_and_or_b32 v21, v67, s77, v18
	v_and_b32_e32 v18, 0xffff, v64
	s_waitcnt vmcnt(12)
	v_and_or_b32 v22, v65, s77, v19
	s_waitcnt vmcnt(11)
	v_and_b32_e32 v19, 0xffff, v62
	s_waitcnt vmcnt(9)
	v_lshrrev_b32_e32 v25, 16, v60
	s_waitcnt vmcnt(7)
	v_lshrrev_b32_e32 v26, 16, v58
	s_waitcnt vmcnt(5)
	v_lshrrev_b32_e32 v27, 16, v56
	v_lshl_or_b32 v16, v69, 16, v16
	v_lshl_or_b32 v17, v67, 16, v17
	v_lshl_or_b32 v18, v65, 16, v18
	v_lshl_or_b32 v19, v63, 16, v19
	v_lshrrev_b32_e32 v23, 16, v62
	v_and_b32_e32 v24, 0xffff, v60
	v_and_or_b32 v28, v61, s77, v25
	v_and_b32_e32 v25, 0xffff, v58
	v_and_or_b32 v29, v59, s77, v26
	v_and_b32_e32 v26, 0xffff, v56
	s_waitcnt vmcnt(4)
	v_and_or_b32 v30, v57, s77, v27
	s_waitcnt vmcnt(3)
	v_and_b32_e32 v27, 0xffff, v54
	v_lshrrev_b32_e32 v31, 16, v54
	v_add3_u32 v54, s15, v205, v204
	v_and_or_b32 v23, v63, s77, v23
	v_lshl_or_b32 v24, v61, 16, v24
	v_lshl_or_b32 v25, v59, 16, v25
	v_lshl_or_b32 v26, v57, 16, v26
	s_waitcnt vmcnt(2)
	v_lshl_or_b32 v27, v55, 16, v27
	v_and_or_b32 v31, v55, s77, v31
	ds_write_b128 v54, v[16:19] offset:18944
	ds_write_b128 v54, v[24:27] offset:18960
	ds_write_b128 v54, v[20:23] offset:19024
	ds_write_b128 v54, v[28:31] offset:19040
	s_waitcnt lgkmcnt(0)
	s_barrier
	v_add3_u32 v28, s15, v207, v206
	ds_read_b128 v[16:19], v233
	ds_read_b128 v[20:23], v28
	s_waitcnt lgkmcnt(0)
	v_mfma_f32_16x16x32_bf16 v[16:19], v[16:19], v[20:23], 0
	ds_read_b128 v[20:23], v233 offset:64
	ds_read_b128 v[24:27], v28 offset:64
	s_add_i32 s20, s20, 1
	s_add_i32 s8, s8, -1
	s_waitcnt lgkmcnt(0)
	v_mfma_f32_16x16x32_bf16 v[16:19], v[20:23], v[24:27], v[16:19]
	ds_read_b128 v[20:23], v233 offset:128
	ds_read_b128 v[24:27], v28 offset:128
	s_cmp_eq_u32 s20, 64
	s_waitcnt lgkmcnt(0)
	v_mfma_f32_16x16x32_bf16 v[16:19], v[20:23], v[24:27], v[16:19]
	ds_read_b128 v[20:23], v233 offset:192
	ds_read_b128 v[24:27], v28 offset:192
	s_waitcnt lgkmcnt(0)
	v_mfma_f32_16x16x32_bf16 v[16:19], v[20:23], v[24:27], v[16:19]
	s_nop 7
	v_cndmask_b32_e64 v16, 0, v16, s[50:51]
	v_cndmask_b32_e64 v17, 0, v17, s[52:53]
	v_cndmask_b32_e64 v18, 0, v18, s[54:55]
	v_cndmask_b32_e64 v19, 0, v19, s[56:57]
	v_cvt_pk_bf16_f32 v16, v16, v17
	v_cvt_pk_bf16_f32 v17, v18, v19
	v_add3_u32 v18, s15, v208, v209
	ds_write_b64 v18, v[16:17] offset:39424
	s_waitcnt lgkmcnt(0)
	s_barrier
	s_cbranch_scc1 .LBB0_211
; __device__ __forceinline__ void gla_scan_phase2(LAS unsigned char* lds, const bf16_t* proj, const float* gbuf, const float* wgu  , const float* bg  ,
;                                                 bf16_t* ob0, bf16_t* ob1) {
;     ...
;                 if (n < NCH) {
;                     const int tok0 = b * SEQ + (dir ? NCH - 1 - n : n) * CH;
;                     LAS unsigned char* set = lds + (n & 1) * G2_SET;
;                     const f32x4 ga = gna, gb = gnb;
;                     const unsigned srow = (unsigned)tok0 * (unsigned)(GINP * 2);
;                     unsigned short qv[16], kv[16];
; #pragma unroll
;                     for (int ii = 0; ii < 16; ++ii) { qv[ii] = __builtin_amdgcn_raw_buffer_load_b16(prs, qvoff, srow + (unsigned)(ii * GINP * 2), 0);
;                                                        kv[ii] = __builtin_amdgcn_raw_buffer_load_b16(prs, qvoff + 1024u, srow + (unsigned)(ii * GINP * 2), 0); }
;                     unsigned vw[16];
; #pragma unroll
;                     for (int ii = 0; ii < 16; ++ii) vw[ii] = __builtin_amdgcn_raw_buffer_load_b32(prs, vvoff, srow + (unsigned)(ii * GINP * 2), 0);
;                     { const int n1 = n + 1 < NCH ? n + 1 : n; const float* grow = gbuf + (size_t)(b * SEQ + (dir ? NCH - 1 - n1 : n1) * CH + r) * 32 + dir * 16 + 8 * hh;
;                       gna = *(const f32x4*)grow; gnb = *(const f32x4*)(grow + 4); }
;                     {
;                         u32x4 ah, al;
;                         ah.x = pk2(ga[0], ga[1]); ah.y = pk2(ga[2], ga[3]); ah.z = pk2(gb[0], gb[1]); ah.w = pk2(gb[2], gb[3]);
;                         al.x = pk2(ga[0] - bflo(ah.x), ga[1] - bfhi(ah.x)); al.y = pk2(ga[2] - bflo(ah.y), ga[3] - bfhi(ah.y));
;                         al.z = pk2(gb[0] - bflo(ah.z), gb[1] - bfhi(ah.z)); al.w = pk2(gb[2] - bflo(ah.w), gb[3] - bfhi(ah.w));
;                         const bf16x8 gah = __builtin_bit_cast(bf16x8, ah), gal = __builtin_bit_cast(bf16x8, al);
;                         f32x16 zacc;
; #pragma unroll
;                         for (int i = 0; i < 16; ++i) zacc[i] = zbias;
;                         zacc = MFMA32(gah, wbh, zacc); zacc = MFMA32(gal, wbh, zacc); zacc = MFMA32(gah, wbl, zacc);
; #pragma unroll
;                         for (int i = 0; i < 16; ++i) *(LAS float*)(lds + G2_Z + (((i & 3) + 8 * (i >> 2) + 4 * hh) * 128 + 32 * zd + r) * 4) = zacc[i];
.LBB0_220:
	s_waitcnt vmcnt(0)
	v_cvt_pk_bf16_f32 v102, v44, v45
	v_lshlrev_b32_e32 v16, 16, v102
	v_and_b32_e32 v17, 0xffff0000, v102
	v_cvt_pk_bf16_f32 v103, v46, v47
	v_cvt_pk_bf16_f32 v104, v40, v41
	v_cvt_pk_bf16_f32 v105, v42, v43
	v_pk_add_f32 v[16:17], v[44:45], v[16:17] neg_lo:[0,1] neg_hi:[0,1]
	s_and_b64 s[6:7], s[48:49], exec
	v_cvt_pk_bf16_f32 v44, v16, v17
	v_lshlrev_b32_e32 v16, 16, v103
	v_and_b32_e32 v17, 0xffff0000, v103
	v_pk_add_f32 v[16:17], v[46:47], v[16:17] neg_lo:[0,1] neg_hi:[0,1]
	s_cselect_b32 s0, s20, s8
	v_cvt_pk_bf16_f32 v45, v16, v17
	v_lshlrev_b32_e32 v16, 16, v104
	v_and_b32_e32 v17, 0xffff0000, v104
	v_pk_add_f32 v[16:17], v[40:41], v[16:17] neg_lo:[0,1] neg_hi:[0,1]
	v_lshlrev_b32_e32 v40, 16, v105
	v_cvt_pk_bf16_f32 v46, v16, v17
	v_mfma_f32_32x32x16_bf16 v[16:31], v[102:105], v[32:35], v[0:15]
	v_and_b32_e32 v41, 0xffff0000, v105
	v_add_f32_e64 v40, v42, -v40
	v_add_f32_e64 v41, v43, -v41
	s_lshl_b32 s0, s0, 5
	v_cvt_pk_bf16_f32 v47, v40, v41
	s_add_i32 s0, s0, s9
	s_mulk_i32 s0, 0x1a00
	s_or_b32 s6, s0, 0x1a00
	v_mfma_f32_32x32x16_bf16 v[16:31], v[44:47], v[32:35], v[16:31]
	s_or_b32 s7, s0, 0x3400
	s_add_i32 s15, s0, 0x4e00
	s_add_i32 s21, s0, 0x6800
	s_add_i32 s24, s0, 0x8200
	s_add_i32 s25, s0, 0x9c00
	s_add_i32 s26, s0, 0xb600
	s_add_i32 s28, s0, 0xd000
	s_add_i32 s33, s0, 0xea00
	s_add_i32 s78, s0, 0x10400
	s_add_i32 s79, s0, 0x11e00
	s_add_i32 s80, s0, 0x13800
	s_add_i32 s81, s0, 0x15200
	s_add_i32 s82, s0, 0x16c00
	s_add_i32 s83, s0, 0x18600
	s_cmp_lt_u32 s20, 63
	buffer_load_ushort v98, v50, s[64:67], s0 offen
	buffer_load_ushort v100, v50, s[64:67], s6 offen
	buffer_load_ushort v94, v50, s[64:67], s7 offen
	buffer_load_ushort v96, v50, s[64:67], s15 offen
	buffer_load_ushort v90, v50, s[64:67], s21 offen
	buffer_load_ushort v92, v50, s[64:67], s24 offen
	buffer_load_ushort v82, v50, s[64:67], s25 offen
	buffer_load_ushort v84, v50, s[64:67], s26 offen
	buffer_load_ushort v99, v53, s[64:67], s0 offen
	buffer_load_ushort v101, v53, s[64:67], s6 offen
	buffer_load_ushort v95, v53, s[64:67], s7 offen
	buffer_load_ushort v97, v53, s[64:67], s15 offen
	buffer_load_ushort v91, v53, s[64:67], s21 offen
	buffer_load_ushort v93, v53, s[64:67], s24 offen
	buffer_load_ushort v83, v53, s[64:67], s25 offen
	buffer_load_ushort v85, v53, s[64:67], s26 offen
	buffer_load_ushort v86, v50, s[64:67], s28 offen
	buffer_load_ushort v88, v50, s[64:67], s33 offen
	buffer_load_ushort v78, v50, s[64:67], s78 offen
	buffer_load_ushort v80, v50, s[64:67], s79 offen
	buffer_load_ushort v74, v50, s[64:67], s80 offen
	buffer_load_ushort v76, v50, s[64:67], s81 offen
	buffer_load_ushort v70, v50, s[64:67], s82 offen
	buffer_load_ushort v72, v50, s[64:67], s83 offen
	buffer_load_ushort v87, v53, s[64:67], s28 offen
	buffer_load_ushort v89, v53, s[64:67], s33 offen
	buffer_load_ushort v79, v53, s[64:67], s78 offen
	buffer_load_ushort v81, v53, s[64:67], s79 offen
	buffer_load_ushort v75, v53, s[64:67], s80 offen
	buffer_load_ushort v77, v53, s[64:67], s81 offen
	buffer_load_ushort v71, v53, s[64:67], s82 offen
	buffer_load_ushort v73, v53, s[64:67], s83 offen
	buffer_load_dword v68, v51, s[64:67], s0 offen
	buffer_load_dword v69, v51, s[64:67], s6 offen
	buffer_load_dword v66, v51, s[64:67], s7 offen
	buffer_load_dword v67, v51, s[64:67], s15 offen
	buffer_load_dword v64, v51, s[64:67], s21 offen
	buffer_load_dword v65, v51, s[64:67], s24 offen
	buffer_load_dword v62, v51, s[64:67], s25 offen
	buffer_load_dword v63, v51, s[64:67], s26 offen
	buffer_load_dword v60, v51, s[64:67], s28 offen
	buffer_load_dword v61, v51, s[64:67], s33 offen
	buffer_load_dword v58, v51, s[64:67], s78 offen
	buffer_load_dword v59, v51, s[64:67], s79 offen
	buffer_load_dword v56, v51, s[64:67], s80 offen
	buffer_load_dword v57, v51, s[64:67], s81 offen
	buffer_load_dword v54, v51, s[64:67], s82 offen
	buffer_load_dword v55, v51, s[64:67], s83 offen
	s_cselect_b64 s[6:7], -1, 0
	s_cmp_lg_u64 s[6:7], 0
	s_addc_u32 s0, s20, 0
	s_cmp_lg_u64 s[6:7], 0
	s_subb_u32 s6, 0, 0
	v_mfma_f32_32x32x16_bf16 v[16:31], v[102:105], v[36:39], v[16:31]
	s_add_i32 s15, s8, s6
	s_and_b64 s[6:7], s[48:49], exec
	s_cselect_b32 s0, s0, s15
	v_lshl_add_u32 v40, s0, 5, v52
	v_ashrrev_i32_e32 v41, 31, v40
	v_lshlrev_b64 v[40:41], 7, v[40:41]
	v_lshl_add_u64 v[44:45], v[48:49], 0, v[40:41]
	global_load_dwordx4 v[40:43], v[44:45], off offset:16
	s_nop 0
	global_load_dwordx4 v[44:47], v[44:45], off
	s_nop 1
	ds_write_b32 v214, v16
	ds_write_b32 v215, v17
	ds_write_b32 v216, v18
	ds_write_b32 v217, v19
	ds_write_b32 v218, v20
	ds_write_b32 v219, v21
	ds_write_b32 v220, v22
	ds_write_b32 v221, v23
	ds_write_b32 v222, v24
	ds_write_b32 v223, v25
	ds_write_b32 v224, v26
	ds_write_b32 v225, v27
	ds_write_b32 v226, v28
	ds_write_b32 v227, v29
	ds_write_b32 v228, v30
	ds_write_b32 v229, v31
	s_waitcnt lgkmcnt(0)
	s_barrier
; #define LAS __attribute__((address_space(3)))
; __device__ __forceinline__ void gla_scan_phase2(LAS unsigned char* lds, const bf16_t* proj, const float* gbuf, const float* wgu  , const float* bg  ,
;                                                 bf16_t* ob0, bf16_t* ob1) {
;     ...
;                     float cs[16];
; #pragma unroll
;                     for (int ii = 0; ii < 16; ++ii) {
;                         const float z = *(const LAS float*)(lds + G2_Z + ((16 * seg + ii) * 128 + d) * 4);
;                         cs[ii] = fminf(z, 0.f) * (1.4426950408889634f / 16.f) - __builtin_amdgcn_logf(1.f + __builtin_amdgcn_exp2f(fabsf(z) * -1.4426950408889634f)) * (1.f / 16.f);
;                     }
;                     if (dir == 0) {
; #pragma unroll
;                         for (int ii = 1; ii < 16; ++ii) cs[ii] += cs[ii - 1];
;                         *(LAS float*)(lds + G2_SEG + (seg * 128 + d) * 4) = cs[15];
;                     } else {
; #pragma unroll
;     ...
;                         *(LAS float*)(lds + G2_SEG + (seg * 128 + d) * 4) = cs[0];
;                     }
	ds_read2st64_b32 v[16:17], v230 offset1:2
	s_andn2_b64 vcc, exec, s[68:69]
	s_mov_b64 s[6:7], -1
	s_waitcnt lgkmcnt(0)
	v_mul_f32_e64 v18, |v16|, s1
	v_exp_f32_e32 v18, v18
	v_max_f32_e32 v16, v16, v16
	v_min_f32_e32 v16, 0, v16
	v_add_f32_e32 v18, 1.0, v18
	v_log_f32_e32 v18, v18
	s_nop 0
	v_mul_f32_e32 v20, 0x3d800000, v18
	v_mul_f32_e64 v18, |v17|, s1
	v_exp_f32_e32 v21, v18
	v_fma_f32 v16, v16, s10, -v20
	ds_read2st64_b32 v[18:19], v230 offset0:4 offset1:6
	v_max_f32_e32 v17, v17, v17
	v_add_f32_e32 v20, 1.0, v21
	v_log_f32_e32 v20, v20
	v_min_f32_e32 v17, 0, v17
	s_waitcnt lgkmcnt(0)
	v_mul_f32_e64 v21, |v18|, s1
	v_exp_f32_e32 v21, v21
	v_mul_f32_e32 v20, 0x3d800000, v20
	v_fma_f32 v25, v17, s10, -v20
	v_mul_f32_e64 v20, |v19|, s1
	v_exp_f32_e32 v20, v20
	v_add_f32_e32 v17, 1.0, v21
	v_log_f32_e32 v17, v17
	v_max_f32_e32 v18, v18, v18
	v_add_f32_e32 v20, 1.0, v20
	v_log_f32_e32 v22, v20
	ds_read2st64_b32 v[20:21], v230 offset0:8 offset1:10
	v_min_f32_e32 v18, 0, v18
	v_mul_f32_e32 v17, 0x3d800000, v17
	v_fma_f32 v26, v18, s10, -v17
	v_max_f32_e32 v17, v19, v19
	s_waitcnt lgkmcnt(0)
	v_mul_f32_e64 v19, |v20|, s1
	v_exp_f32_e32 v19, v19
	v_min_f32_e32 v17, 0, v17
	v_mul_f32_e32 v18, 0x3d800000, v22
	v_fma_f32 v29, v17, s10, -v18
	v_add_f32_e32 v18, 1.0, v19
	v_max_f32_e32 v17, v20, v20
	v_log_f32_e32 v20, v18
	v_mul_f32_e64 v18, |v21|, s1
	v_exp_f32_e32 v22, v18
	ds_read2st64_b32 v[18:19], v230 offset0:12 offset1:14
	v_min_f32_e32 v17, 0, v17
	v_mul_f32_e32 v20, 0x3d800000, v20
	v_fma_f32 v30, v17, s10, -v20
	v_add_f32_e32 v17, 1.0, v22
	s_waitcnt lgkmcnt(0)
	v_mul_f32_e64 v20, |v18|, s1
	v_exp_f32_e32 v20, v20
	v_log_f32_e32 v17, v17
	v_max_f32_e32 v21, v21, v21
	v_min_f32_e32 v21, 0, v21
	v_add_f32_e32 v20, 1.0, v20
	v_log_f32_e32 v20, v20
	v_mul_f32_e32 v17, 0x3d800000, v17
	v_fma_f32 v102, v21, s10, -v17
	v_max_f32_e32 v17, v18, v18
	v_mul_f32_e32 v18, 0x3d800000, v20
	v_mul_f32_e64 v20, |v19|, s1
	v_exp_f32_e32 v22, v20
	v_min_f32_e32 v17, 0, v17
	v_fma_f32 v104, v17, s10, -v18
	ds_read2st64_b32 v[20:21], v230 offset0:16 offset1:18
	v_add_f32_e32 v18, 1.0, v22
	v_log_f32_e32 v18, v18
	v_max_f32_e32 v17, v19, v19
	v_min_f32_e32 v17, 0, v17
	s_waitcnt lgkmcnt(0)
	v_mul_f32_e64 v19, |v20|, s1
	v_mul_f32_e32 v18, 0x3d800000, v18
	v_fma_f32 v105, v17, s10, -v18
	v_mul_f32_e64 v18, |v21|, s1
	v_exp_f32_e32 v19, v19
	v_exp_f32_e32 v18, v18
	v_add_f32_e32 v17, 1.0, v19
	v_max_f32_e32 v19, v20, v20
	v_add_f32_e32 v18, 1.0, v18
	v_log_f32_e32 v17, v17
	v_min_f32_e32 v20, 0, v19
	v_log_f32_e32 v22, v18
	ds_read2st64_b32 v[18:19], v230 offset0:20 offset1:22
	v_mul_f32_e32 v17, 0x3d800000, v17
	v_fma_f32 v108, v20, s10, -v17
	v_max_f32_e32 v17, v21, v21
	v_min_f32_e32 v17, 0, v17
	s_waitcnt lgkmcnt(0)
	v_mul_f32_e64 v21, |v18|, s1
	v_exp_f32_e32 v21, v21
	v_mul_f32_e32 v20, 0x3d800000, v22
	v_fma_f32 v109, v17, s10, -v20
	v_max_f32_e32 v17, v18, v18
	v_add_f32_e32 v18, 1.0, v21
	v_mul_f32_e64 v20, |v19|, s1
	v_log_f32_e32 v18, v18
	v_exp_f32_e32 v22, v20
	ds_read2st64_b32 v[20:21], v230 offset0:24 offset1:26
	v_min_f32_e32 v17, 0, v17
	v_mul_f32_e32 v18, 0x3d800000, v18
	v_fma_f32 v111, v17, s10, -v18
	v_add_f32_e32 v17, 1.0, v22
	s_waitcnt lgkmcnt(0)
	v_mul_f32_e64 v18, |v20|, s1
	v_exp_f32_e32 v18, v18
	v_log_f32_e32 v17, v17
	v_max_f32_e32 v19, v19, v19
	v_min_f32_e32 v19, 0, v19
	v_add_f32_e32 v18, 1.0, v18
	v_log_f32_e32 v18, v18
	v_mul_f32_e32 v17, 0x3d800000, v17
	v_fma_f32 v112, v19, s10, -v17
	v_max_f32_e32 v17, v20, v20
	v_mul_f32_e32 v20, 0x3d800000, v18
	v_mul_f32_e64 v18, |v21|, s1
	v_exp_f32_e32 v22, v18
	v_min_f32_e32 v17, 0, v17
	ds_read2st64_b32 v[18:19], v230 offset0:28 offset1:30
	v_fma_f32 v113, v17, s10, -v20
	v_add_f32_e32 v20, 1.0, v22
	v_log_f32_e32 v20, v20
	v_max_f32_e32 v17, v21, v21
	s_waitcnt lgkmcnt(0)
	v_mul_f32_e64 v21, |v18|, s1
	v_exp_f32_e32 v21, v21
	v_min_f32_e32 v17, 0, v17
	v_mul_f32_e32 v20, 0x3d800000, v20
	v_fma_f32 v114, v17, s10, -v20
	v_mul_f32_e64 v20, |v19|, s1
	v_exp_f32_e32 v20, v20
	v_add_f32_e32 v17, 1.0, v21
	v_log_f32_e32 v17, v17
	v_max_f32_e32 v18, v18, v18
	v_add_f32_e32 v20, 1.0, v20
	v_log_f32_e32 v20, v20
	v_min_f32_e32 v18, 0, v18
	v_mul_f32_e32 v17, 0x3d800000, v17
	v_fma_f32 v116, v18, s10, -v17
	v_max_f32_e32 v17, v19, v19
	v_min_f32_e32 v17, 0, v17
	v_mul_f32_e32 v18, 0x3d800000, v20
	v_fma_f32 v17, v17, s10, -v18
	s_cbranch_vccnz .LBB0_222
	v_add_f32_e32 v18, v116, v17
	v_add_f32_e32 v19, v114, v18
	v_add_f32_e32 v20, v113, v19
	v_add_f32_e32 v21, v112, v20
	v_add_f32_e32 v22, v111, v21
	v_add_f32_e32 v23, v109, v22
	v_add_f32_e32 v24, v108, v23
	v_add_f32_e32 v27, v105, v24
	v_add_f32_e32 v28, v104, v27
	v_add_f32_e32 v31, v102, v28
	v_add_f32_e32 v103, v30, v31
	v_add_f32_e32 v106, v29, v103
	v_add_f32_e32 v107, v26, v106
	v_add_f32_e32 v110, v25, v107
	v_add_f32_e32 v115, v16, v110
	s_mov_b64 s[6:7], 0

; #define LAS __attribute__((address_space(3)))
; __device__ __forceinline__ unsigned pk2(float lo, float hi) { f32x2 v = {lo, hi}; bf16x2_t b = __builtin_convertvector(v, bf16x2_t); return __builtin_bit_cast(unsigned, b); }
; __device__ __forceinline__ float bflo(unsigned w) { return __uint_as_float(w << 16); }
; __device__ __forceinline__ float bfhi(unsigned w) { return __uint_as_float(w & 0xffff0000u); }
;     __device__ __forceinline__ void operator()(const f32x4 (&acc)[2][2][4][2], const Unit& u, int wr, int wc, int fr, int fq, LAS unsigned char* lds, int tid, State& st) const {
;         const int col0 = u.pn * BM + wc * 32 + 8 * fq;
;         LAS float* RED = (LAS float*)(lds + STAGE_BYTES);
; #pragma unroll
;         for (int ai = 0; ai < 2; ++ai) {
;             u32x4 bw[4][2];
; #pragma unroll
;             for (int m = 0; m < 4; ++m)
; #pragma unroll
;                 for (int bj = 0; bj < 2; ++bj) bw[m][bj] = *(const u32x4*)(xin + (size_t)(u.pm * BM + ai * HALF + wr * 64 + m * 16 + fr) * DM + col0 + bj * HALF);
; #pragma unroll
;             for (int m = 0; m < 4; ++m) {
;                 const int rl = ai * HALF + wr * 64 + m * 16 + fr;
;                 bf16_t* xp = xb + (size_t)(u.pm * BM + rl) * DM + col0;
;                 float sq = 0.f;
; #pragma unroll
;                 for (int bj = 0; bj < 2; ++bj) {
;                     const u32x4 w0 = bw[m][bj];
;                     const f32x4 o0 = (f32x4){bflo(w0.x), bfhi(w0.x), bflo(w0.y), bfhi(w0.y)} + acc[ai][bj][m][0];
;                     const f32x4 o1 = (f32x4){bflo(w0.z), bfhi(w0.z), bflo(w0.w), bfhi(w0.w)} + acc[ai][bj][m][1];
;                     sq += ((o0[0] * o0[0] + o0[1] * o0[1]) + (o0[2] * o0[2] + o0[3] * o0[3])) + ((o1[0] * o1[0] + o1[1] * o1[1]) + (o1[2] * o1[2] + o1[3] * o1[3]));
;                     u32x4 w; w.x = pk2(o0[0], o0[1]); w.y = pk2(o0[2], o0[3]); w.z = pk2(o1[0], o1[1]); w.w = pk2(o1[2], o1[3]);
;                     *(u32x4*)(xp + bj * HALF) = w;
;                 }
;                 sq += __shfl_xor(sq, 16); sq += __shfl_xor(sq, 32);
;                 if (fq == 0) RED[wc * 256 + rl] = sq;
.LBB0_810:
	v_and_b32_e32 v129, 64, v194
	v_xor_b32_e32 v128, 16, v194
	v_add_u32_e32 v129, 64, v129
	v_cmp_lt_i32_e32 vcc, v128, v129
	v_lshl_or_b32 v168, s12, 8, v188
	s_lshl_b32 s13, s13, 8
	v_cndmask_b32_e32 v128, v194, v128, vcc
	v_add_u32_e32 v170, s13, v177
	v_ashrrev_i32_e32 v169, 31, v168
	v_lshlrev_b32_e32 v198, 2, v128
	v_xor_b32_e32 v128, 32, v194
	v_cmp_lt_i32_e32 vcc, v128, v129
	v_lshlrev_b64 v[174:175], 1, v[168:169]
	v_ashrrev_i32_e32 v171, 31, v170
	v_cndmask_b32_e32 v128, v194, v128, vcc
	v_lshl_add_u64 v[172:173], s[84:85], 0, v[174:175]
	v_lshlrev_b64 v[204:205], 11, v[170:171]
	v_lshlrev_b32_e32 v197, 2, v128
	v_lshl_add_u64 v[128:129], v[172:173], 0, v[204:205]
	global_load_dwordx4 v[200:203], v[128:129], off
	global_load_dwordx4 v[152:155], v[128:129], off offset:256
	v_or_b32_e32 v128, 16, v170
	v_ashrrev_i32_e32 v129, 31, v128
	v_lshlrev_b64 v[128:129], 11, v[128:129]
	v_lshl_add_u64 v[128:129], v[172:173], 0, v[128:129]
	global_load_dwordx4 v[148:151], v[128:129], off
	global_load_dwordx4 v[144:147], v[128:129], off offset:256
	v_or_b32_e32 v128, 32, v170
	v_ashrrev_i32_e32 v129, 31, v128
	v_lshlrev_b64 v[128:129], 11, v[128:129]
	v_lshl_add_u64 v[128:129], v[172:173], 0, v[128:129]
	global_load_dwordx4 v[140:143], v[128:129], off
	global_load_dwordx4 v[136:139], v[128:129], off offset:256
	v_or_b32_e32 v128, 48, v170
	v_ashrrev_i32_e32 v129, 31, v128
	v_lshlrev_b64 v[128:129], 11, v[128:129]
	v_lshl_add_u64 v[128:129], v[172:173], 0, v[128:129]
	global_load_dwordx4 v[132:135], v[128:129], off
	s_nop 0
	global_load_dwordx4 v[128:131], v[128:129], off offset:256
	v_lshl_add_u64 v[204:205], s[84:85], 0, v[204:205]
	v_lshl_add_u64 v[174:175], v[204:205], 0, v[174:175]
	v_add_u32_e32 v234, 0x80, v170
	v_ashrrev_i32_e32 v235, 31, v234
	v_lshlrev_b64 v[234:235], 11, v[234:235]
	v_lshl_add_u64 v[234:235], v[172:173], 0, v[234:235]
	global_load_dwordx4 v[206:209], v[234:235], off
	global_load_dwordx4 v[210:213], v[234:235], off offset:256
	v_add_u32_e32 v234, 0x90, v170
	v_ashrrev_i32_e32 v235, 31, v234
	v_lshlrev_b64 v[234:235], 11, v[234:235]
	v_lshl_add_u64 v[234:235], v[172:173], 0, v[234:235]
	global_load_dwordx4 v[214:217], v[234:235], off
	global_load_dwordx4 v[218:221], v[234:235], off offset:256
	v_add_u32_e32 v234, 0xa0, v170
	v_ashrrev_i32_e32 v235, 31, v234
	v_lshlrev_b64 v[234:235], 11, v[234:235]
	v_lshl_add_u64 v[234:235], v[172:173], 0, v[234:235]
	global_load_dwordx4 v[222:225], v[234:235], off
	global_load_dwordx4 v[226:229], v[234:235], off offset:256
	v_add_u32_e32 v234, 0xb0, v170
	v_ashrrev_i32_e32 v235, 31, v234
	v_lshlrev_b64 v[234:235], 11, v[234:235]
	v_lshl_add_u64 v[234:235], v[172:173], 0, v[234:235]
	global_load_dwordx4 v[230:233], v[234:235], off
	s_waitcnt vmcnt(7)
	v_lshlrev_b32_e32 v204, 16, v200
	v_and_b32_e32 v205, 0xffff0000, v200
	v_lshlrev_b32_e32 v200, 16, v201
	v_and_b32_e32 v201, 0xffff0000, v201
	v_pk_add_f32 v[126:127], v[126:127], v[200:201]
	v_pk_add_f32 v[124:125], v[124:125], v[204:205]
	v_lshlrev_b32_e32 v200, 16, v202
	v_and_b32_e32 v201, 0xffff0000, v202
	v_lshlrev_b32_e32 v202, 16, v203
	v_and_b32_e32 v203, 0xffff0000, v203
	v_pk_add_f32 v[202:203], v[122:123], v[202:203]
	v_pk_add_f32 v[122:123], v[120:121], v[200:201]
	v_mul_f32_e32 v120, v125, v125
	v_mul_f32_e32 v121, v127, v127
	v_fmac_f32_e32 v120, v124, v124
	v_fmac_f32_e32 v121, v126, v126
	v_add_f32_e32 v120, v120, v121
	v_mul_f32_e32 v121, v123, v123
	v_mul_f32_e32 v171, v203, v203
	v_fmac_f32_e32 v121, v122, v122
	v_fmac_f32_e32 v171, v202, v202
	v_add_f32_e32 v121, v121, v171
	v_add_f32_e32 v171, v120, v121
	v_cvt_pk_bf16_f32 v120, v124, v125
	v_cvt_pk_bf16_f32 v121, v126, v127
	v_cvt_pk_bf16_f32 v122, v122, v123
	v_cvt_pk_bf16_f32 v123, v202, v203
	global_load_dwordx4 v[200:203], v[234:235], off offset:256
	global_store_dwordx4 v[174:175], v[120:123], off
	s_nop 1
	v_lshlrev_b32_e32 v120, 16, v152
	v_and_b32_e32 v121, 0xffff0000, v152
	v_lshlrev_b32_e32 v122, 16, v153
	v_and_b32_e32 v123, 0xffff0000, v153
	v_pk_add_f32 v[118:119], v[118:119], v[122:123]
	v_pk_add_f32 v[116:117], v[116:117], v[120:121]
	v_lshlrev_b32_e32 v120, 16, v154
	v_and_b32_e32 v121, 0xffff0000, v154
	v_lshlrev_b32_e32 v122, 16, v155
	v_and_b32_e32 v123, 0xffff0000, v155
	v_pk_add_f32 v[122:123], v[114:115], v[122:123]
	v_pk_add_f32 v[114:115], v[112:113], v[120:121]
	v_mul_f32_e32 v112, v117, v117
	v_mul_f32_e32 v113, v119, v119
	v_fmac_f32_e32 v112, v116, v116
	v_fmac_f32_e32 v113, v118, v118
	v_add_f32_e32 v112, v112, v113
	v_mul_f32_e32 v113, v115, v115
	v_mul_f32_e32 v120, v123, v123
	v_fmac_f32_e32 v113, v114, v114
	v_fmac_f32_e32 v120, v122, v122
	v_add_f32_e32 v113, v113, v120
	v_add_f32_e32 v112, v112, v113
	v_add_f32_e32 v120, v171, v112
	v_cvt_pk_bf16_f32 v112, v116, v117
	v_cvt_pk_bf16_f32 v113, v118, v119
	v_cvt_pk_bf16_f32 v114, v114, v115
	v_cvt_pk_bf16_f32 v115, v122, v123
	global_store_dwordx4 v[174:175], v[112:115], off offset:256
	ds_bpermute_b32 v112, v198, v120
	s_waitcnt lgkmcnt(0)
	v_add_f32_e32 v112, v120, v112
	ds_bpermute_b32 v113, v197, v112
	s_and_saveexec_b64 s[6:7], s[38:39]
	s_cbranch_execz .LBB0_812
	s_waitcnt lgkmcnt(0)
	v_add_f32_e32 v112, v112, v113
	ds_write_b32 v190, v112

; __device__ __forceinline__ unsigned pk2(float lo, float hi) { f32x2 v = {lo, hi}; bf16x2_t b = __builtin_convertvector(v, bf16x2_t); return __builtin_bit_cast(unsigned, b); }
; __device__ __forceinline__ float bflo(unsigned w) { return __uint_as_float(w << 16); }
; __device__ __forceinline__ float bfhi(unsigned w) { return __uint_as_float(w & 0xffff0000u); }
;     __device__ __forceinline__ void operator()(const f32x4 (&acc)[2][2][4][2], const Unit& u, int wr, int wc, int fr, int fq, LAS unsigned char* lds, int tid, State& st) const {
;     ...
;                 for (int bj = 0; bj < 2; ++bj) bw[m][bj] = *(const u32x4*)(xin + (size_t)(u.pm * BM + ai * HALF + wr * 64 + m * 16 + fr) * DM + col0 + bj * HALF);
; #pragma unroll
;             for (int m = 0; m < 4; ++m) {
;                 const int rl = ai * HALF + wr * 64 + m * 16 + fr;
;                 bf16_t* xp = xb + (size_t)(u.pm * BM + rl) * DM + col0;
;                 float sq = 0.f;
; #pragma unroll
;                 for (int bj = 0; bj < 2; ++bj) {
;                     const u32x4 w0 = bw[m][bj];
;                     const f32x4 o0 = (f32x4){bflo(w0.x), bfhi(w0.x), bflo(w0.y), bfhi(w0.y)} + acc[ai][bj][m][0];
;                     const f32x4 o1 = (f32x4){bflo(w0.z), bfhi(w0.z), bflo(w0.w), bfhi(w0.w)} + acc[ai][bj][m][1];
;                     sq += ((o0[0] * o0[0] + o0[1] * o0[1]) + (o0[2] * o0[2] + o0[3] * o0[3])) + ((o1[0] * o1[0] + o1[1] * o1[1]) + (o1[2] * o1[2] + o1[3] * o1[3]));
;                     u32x4 w; w.x = pk2(o0[0], o0[1]); w.y = pk2(o0[2], o0[3]); w.z = pk2(o1[0], o1[1]); w.w = pk2(o1[2], o1[3]);
;                     *(u32x4*)(xp + bj * HALF) = w;
;                 }
;                 sq += __shfl_xor(sq, 16); sq += __shfl_xor(sq, 32);
;                 if (fq == 0) RED[wc * 256 + rl] = sq;
.LBB0_818:
	s_or_b64 exec, exec, s[6:7]
	v_add_u32_e32 v64, 0x80, v170
	s_waitcnt lgkmcnt(0)
	v_ashrrev_i32_e32 v65, 31, v64
	v_lshlrev_b64 v[98:99], 11, v[64:65]
	v_lshl_add_u64 v[64:65], v[172:173], 0, v[98:99]
	s_waitcnt vmcnt(8)
	v_mov_b32_e32 v100, v206
	v_mov_b32_e32 v101, v207
	v_mov_b32_e32 v102, v208
	v_mov_b32_e32 v103, v209
	v_mov_b32_e32 v88, v210
	v_mov_b32_e32 v89, v211
	v_mov_b32_e32 v90, v212
	v_mov_b32_e32 v91, v213
	v_add_u32_e32 v64, 0x90, v170
	v_ashrrev_i32_e32 v65, 31, v64
	v_lshlrev_b64 v[96:97], 11, v[64:65]
	v_lshl_add_u64 v[64:65], v[172:173], 0, v[96:97]
	v_mov_b32_e32 v84, v214
	v_mov_b32_e32 v85, v215
	v_mov_b32_e32 v86, v216
	v_mov_b32_e32 v87, v217
	v_mov_b32_e32 v80, v218
	v_mov_b32_e32 v81, v219
	v_mov_b32_e32 v82, v220
	v_mov_b32_e32 v83, v221
	v_add_u32_e32 v64, 0xa0, v170
	v_ashrrev_i32_e32 v65, 31, v64
	v_lshlrev_b64 v[94:95], 11, v[64:65]
	v_lshl_add_u64 v[64:65], v[172:173], 0, v[94:95]
	v_mov_b32_e32 v76, v222
	v_mov_b32_e32 v77, v223
	v_mov_b32_e32 v78, v224
	v_mov_b32_e32 v79, v225
	v_mov_b32_e32 v72, v226
	v_mov_b32_e32 v73, v227
	v_mov_b32_e32 v74, v228
	v_mov_b32_e32 v75, v229
	v_add_u32_e32 v64, 0xb0, v170
	v_ashrrev_i32_e32 v65, 31, v64
	v_lshlrev_b64 v[92:93], 11, v[64:65]
	v_lshl_add_u64 v[64:65], v[172:173], 0, v[92:93]
	v_mov_b32_e32 v68, v230
	v_mov_b32_e32 v69, v231
	v_mov_b32_e32 v70, v232
	v_mov_b32_e32 v71, v233
	s_nop 0
	v_mov_b32_e32 v64, v200
	v_mov_b32_e32 v65, v201
	v_mov_b32_e32 v66, v202
	v_mov_b32_e32 v67, v203
	v_lshl_add_u64 v[98:99], s[84:85], 0, v[98:99]
	v_lshl_add_u64 v[98:99], v[168:169], 1, v[98:99]
	s_nop 0
	v_lshlrev_b32_e32 v104, 16, v100
	v_and_b32_e32 v105, 0xffff0000, v100
	v_lshlrev_b32_e32 v100, 16, v101
	v_and_b32_e32 v101, 0xffff0000, v101
	v_pk_add_f32 v[62:63], v[62:63], v[100:101]
	v_pk_add_f32 v[60:61], v[60:61], v[104:105]
	v_lshlrev_b32_e32 v100, 16, v102
	v_and_b32_e32 v101, 0xffff0000, v102
	v_lshlrev_b32_e32 v102, 16, v103
	v_and_b32_e32 v103, 0xffff0000, v103
	v_pk_add_f32 v[102:103], v[58:59], v[102:103]
	v_pk_add_f32 v[58:59], v[56:57], v[100:101]
	v_mul_f32_e32 v56, v61, v61
	v_mul_f32_e32 v57, v63, v63
	v_fmac_f32_e32 v56, v60, v60
	v_fmac_f32_e32 v57, v62, v62
	v_add_f32_e32 v56, v56, v57
	v_mul_f32_e32 v57, v59, v59
	v_mul_f32_e32 v100, v103, v103
	v_fmac_f32_e32 v57, v58, v58
	v_fmac_f32_e32 v100, v102, v102
	v_add_f32_e32 v57, v57, v100
	v_add_f32_e32 v100, v56, v57
	v_cvt_pk_bf16_f32 v56, v60, v61
	v_cvt_pk_bf16_f32 v57, v62, v63
	v_cvt_pk_bf16_f32 v58, v58, v59
	v_cvt_pk_bf16_f32 v59, v102, v103
	global_store_dwordx4 v[98:99], v[56:59], off
	s_nop 0
	s_nop 0
	v_lshlrev_b32_e32 v56, 16, v88
	v_and_b32_e32 v57, 0xffff0000, v88
	v_lshlrev_b32_e32 v58, 16, v89
	v_and_b32_e32 v59, 0xffff0000, v89
	v_pk_add_f32 v[54:55], v[54:55], v[58:59]
	v_pk_add_f32 v[52:53], v[52:53], v[56:57]
	v_lshlrev_b32_e32 v56, 16, v90
	v_and_b32_e32 v57, 0xffff0000, v90
	v_lshlrev_b32_e32 v58, 16, v91
	v_and_b32_e32 v59, 0xffff0000, v91
	v_pk_add_f32 v[58:59], v[50:51], v[58:59]
	v_pk_add_f32 v[50:51], v[48:49], v[56:57]
	v_mul_f32_e32 v48, v53, v53
	v_mul_f32_e32 v49, v55, v55
	v_fmac_f32_e32 v48, v52, v52
	v_fmac_f32_e32 v49, v54, v54
	v_add_f32_e32 v48, v48, v49
	v_mul_f32_e32 v49, v51, v51
	v_mul_f32_e32 v56, v59, v59
	v_fmac_f32_e32 v49, v50, v50
	v_fmac_f32_e32 v56, v58, v58
	v_add_f32_e32 v49, v49, v56
	v_add_f32_e32 v48, v48, v49
	v_add_f32_e32 v56, v100, v48
	v_cvt_pk_bf16_f32 v48, v52, v53
	v_cvt_pk_bf16_f32 v49, v54, v55
	v_cvt_pk_bf16_f32 v50, v50, v51
	v_cvt_pk_bf16_f32 v51, v58, v59
	global_store_dwordx4 v[98:99], v[48:51], off offset:256
	ds_bpermute_b32 v48, v198, v56
	s_waitcnt lgkmcnt(0)
	v_add_f32_e32 v48, v56, v48
	ds_bpermute_b32 v49, v197, v48
	s_and_saveexec_b64 s[6:7], s[38:39]
	s_cbranch_execz .LBB0_820
	s_waitcnt lgkmcnt(0)
	v_add_f32_e32 v48, v48, v49
	ds_write_b32 v190, v48 offset:512
.LBB0_820:
	s_or_b64 exec, exec, s[6:7]
	s_nop 0
	v_lshlrev_b32_e32 v50, 16, v84
	v_and_b32_e32 v51, 0xffff0000, v84
	v_lshlrev_b32_e32 v52, 16, v85
	v_and_b32_e32 v53, 0xffff0000, v85
	v_pk_add_f32 v[46:47], v[46:47], v[52:53]
	v_pk_add_f32 v[44:45], v[44:45], v[50:51]
	v_lshlrev_b32_e32 v50, 16, v86
	v_and_b32_e32 v51, 0xffff0000, v86
	v_lshlrev_b32_e32 v52, 16, v87
	v_and_b32_e32 v53, 0xffff0000, v87
	v_pk_add_f32 v[52:53], v[42:43], v[52:53]
	v_pk_add_f32 v[42:43], v[40:41], v[50:51]
	v_mul_f32_e32 v40, v45, v45
	v_mul_f32_e32 v41, v47, v47
	v_fmac_f32_e32 v40, v44, v44
	v_fmac_f32_e32 v41, v46, v46
	v_add_f32_e32 v40, v40, v41
	v_mul_f32_e32 v41, v43, v43
	v_mul_f32_e32 v50, v53, v53
	v_fmac_f32_e32 v41, v42, v42
	v_fmac_f32_e32 v50, v52, v52
	v_add_f32_e32 v41, v41, v50
	v_add_f32_e32 v50, v40, v41
	v_cvt_pk_bf16_f32 v40, v44, v45
	v_cvt_pk_bf16_f32 v41, v46, v47
	s_nop 0
	v_lshlrev_b32_e32 v44, 16, v80
	v_and_b32_e32 v45, 0xffff0000, v80
	v_lshlrev_b32_e32 v46, 16, v81
	v_and_b32_e32 v47, 0xffff0000, v81
	v_pk_add_f32 v[38:39], v[38:39], v[46:47]
	v_pk_add_f32 v[36:37], v[36:37], v[44:45]
	v_lshlrev_b32_e32 v44, 16, v82
	v_and_b32_e32 v45, 0xffff0000, v82
	v_lshlrev_b32_e32 v46, 16, v83
	v_and_b32_e32 v47, 0xffff0000, v83
	v_pk_add_f32 v[44:45], v[32:33], v[44:45]
	v_mul_f32_e32 v32, v37, v37
	v_mul_f32_e32 v33, v39, v39
	v_pk_add_f32 v[46:47], v[34:35], v[46:47]
	v_fmac_f32_e32 v32, v36, v36
	v_fmac_f32_e32 v33, v38, v38
	v_add_f32_e32 v32, v32, v33
	v_mul_f32_e32 v33, v45, v45
	v_mul_f32_e32 v34, v47, v47
	v_fmac_f32_e32 v33, v44, v44
	v_fmac_f32_e32 v34, v46, v46
	v_add_f32_e32 v33, v33, v34
	v_add_f32_e32 v32, v32, v33
	v_add_f32_e32 v32, v50, v32
	ds_bpermute_b32 v33, v198, v32
	s_waitcnt lgkmcnt(1)
	v_lshl_add_u64 v[48:49], s[84:85], 0, v[96:97]
	v_lshl_add_u64 v[48:49], v[168:169], 1, v[48:49]
	v_cvt_pk_bf16_f32 v42, v42, v43
	v_cvt_pk_bf16_f32 v43, v52, v53
	s_waitcnt lgkmcnt(0)
	v_add_f32_e32 v32, v32, v33
	ds_bpermute_b32 v33, v197, v32
	v_cvt_pk_bf16_f32 v34, v36, v37
	v_cvt_pk_bf16_f32 v35, v38, v39
	v_cvt_pk_bf16_f32 v36, v44, v45
	v_cvt_pk_bf16_f32 v37, v46, v47
	global_store_dwordx4 v[48:49], v[40:43], off
	global_store_dwordx4 v[48:49], v[34:37], off offset:256
	s_and_saveexec_b64 s[6:7], s[38:39]
	s_cbranch_execz .LBB0_822
	s_waitcnt lgkmcnt(0)
	v_add_f32_e32 v32, v32, v33
	ds_write_b32 v190, v32 offset:576
; __device__ __forceinline__ unsigned pk2(float lo, float hi) { f32x2 v = {lo, hi}; bf16x2_t b = __builtin_convertvector(v, bf16x2_t); return __builtin_bit_cast(unsigned, b); }
; __device__ __forceinline__ float bflo(unsigned w) { return __uint_as_float(w << 16); }
; __device__ __forceinline__ float bfhi(unsigned w) { return __uint_as_float(w & 0xffff0000u); }
;     __device__ __forceinline__ void operator()(const f32x4 (&acc)[2][2][4][2], const Unit& u, int wr, int wc, int fr, int fq, LAS unsigned char* lds, int tid, State& st) const {
;     ...
;                 for (int bj = 0; bj < 2; ++bj) bw[m][bj] = *(const u32x4*)(xin + (size_t)(u.pm * BM + ai * HALF + wr * 64 + m * 16 + fr) * DM + col0 + bj * HALF);
; #pragma unroll
;             for (int m = 0; m < 4; ++m) {
;                 const int rl = ai * HALF + wr * 64 + m * 16 + fr;
;                 bf16_t* xp = xb + (size_t)(u.pm * BM + rl) * DM + col0;
;                 float sq = 0.f;
; #pragma unroll
;                 for (int bj = 0; bj < 2; ++bj) {
;                     const u32x4 w0 = bw[m][bj];
;                     const f32x4 o0 = (f32x4){bflo(w0.x), bfhi(w0.x), bflo(w0.y), bfhi(w0.y)} + acc[ai][bj][m][0];
;                     const f32x4 o1 = (f32x4){bflo(w0.z), bfhi(w0.z), bflo(w0.w), bfhi(w0.w)} + acc[ai][bj][m][1];
;                     sq += ((o0[0] * o0[0] + o0[1] * o0[1]) + (o0[2] * o0[2] + o0[3] * o0[3])) + ((o1[0] * o1[0] + o1[1] * o1[1]) + (o1[2] * o1[2] + o1[3] * o1[3]));
;                     u32x4 w; w.x = pk2(o0[0], o0[1]); w.y = pk2(o0[2], o0[3]); w.z = pk2(o1[0], o1[1]); w.w = pk2(o1[2], o1[3]);
;                     *(u32x4*)(xp + bj * HALF) = w;
;                 }
;                 sq += __shfl_xor(sq, 16); sq += __shfl_xor(sq, 32);
;                 if (fq == 0) RED[wc * 256 + rl] = sq;
.LBB0_822:
	s_or_b64 exec, exec, s[6:7]
	s_nop 0
	v_lshlrev_b32_e32 v34, 16, v76
	v_and_b32_e32 v35, 0xffff0000, v76
	v_lshlrev_b32_e32 v36, 16, v77
	v_and_b32_e32 v37, 0xffff0000, v77
	v_pk_add_f32 v[30:31], v[30:31], v[36:37]
	v_pk_add_f32 v[28:29], v[28:29], v[34:35]
	v_lshlrev_b32_e32 v34, 16, v78
	v_and_b32_e32 v35, 0xffff0000, v78
	v_lshlrev_b32_e32 v36, 16, v79
	v_and_b32_e32 v37, 0xffff0000, v79
	v_pk_add_f32 v[36:37], v[26:27], v[36:37]
	v_pk_add_f32 v[26:27], v[24:25], v[34:35]
	v_mul_f32_e32 v24, v29, v29
	v_mul_f32_e32 v25, v31, v31
	v_fmac_f32_e32 v24, v28, v28
	v_fmac_f32_e32 v25, v30, v30
	v_add_f32_e32 v24, v24, v25
	v_mul_f32_e32 v25, v27, v27
	v_mul_f32_e32 v34, v37, v37
	v_fmac_f32_e32 v25, v26, v26
	v_fmac_f32_e32 v34, v36, v36
	v_add_f32_e32 v25, v25, v34
	v_add_f32_e32 v34, v24, v25
	v_cvt_pk_bf16_f32 v24, v28, v29
	v_cvt_pk_bf16_f32 v25, v30, v31
	s_nop 0
	v_lshlrev_b32_e32 v28, 16, v72
	v_and_b32_e32 v29, 0xffff0000, v72
	v_lshlrev_b32_e32 v30, 16, v73
	v_and_b32_e32 v31, 0xffff0000, v73
	v_pk_add_f32 v[22:23], v[22:23], v[30:31]
	v_pk_add_f32 v[20:21], v[20:21], v[28:29]
	v_lshlrev_b32_e32 v28, 16, v74
	v_and_b32_e32 v29, 0xffff0000, v74
	v_lshlrev_b32_e32 v30, 16, v75
	v_and_b32_e32 v31, 0xffff0000, v75
	v_pk_add_f32 v[28:29], v[16:17], v[28:29]
	v_mul_f32_e32 v16, v21, v21
	v_mul_f32_e32 v17, v23, v23
	v_pk_add_f32 v[30:31], v[18:19], v[30:31]
	v_fmac_f32_e32 v16, v20, v20
	v_fmac_f32_e32 v17, v22, v22
	v_add_f32_e32 v16, v16, v17
	v_mul_f32_e32 v17, v29, v29
	v_mul_f32_e32 v18, v31, v31
	v_fmac_f32_e32 v17, v28, v28
	v_fmac_f32_e32 v18, v30, v30
	v_add_f32_e32 v17, v17, v18
	v_add_f32_e32 v16, v16, v17
	v_add_f32_e32 v16, v34, v16
	ds_bpermute_b32 v17, v198, v16
	s_waitcnt lgkmcnt(1)
	v_lshl_add_u64 v[32:33], s[84:85], 0, v[94:95]
	v_lshl_add_u64 v[32:33], v[168:169], 1, v[32:33]
	v_cvt_pk_bf16_f32 v26, v26, v27
	v_cvt_pk_bf16_f32 v27, v36, v37
	s_waitcnt lgkmcnt(0)
	v_add_f32_e32 v16, v16, v17
	ds_bpermute_b32 v17, v197, v16
	v_cvt_pk_bf16_f32 v18, v20, v21
	v_cvt_pk_bf16_f32 v19, v22, v23
	v_cvt_pk_bf16_f32 v20, v28, v29
	v_cvt_pk_bf16_f32 v21, v30, v31
	global_store_dwordx4 v[32:33], v[24:27], off
	global_store_dwordx4 v[32:33], v[18:21], off offset:256
	s_and_saveexec_b64 s[6:7], s[38:39]
	s_cbranch_execz .LBB0_824
	s_waitcnt lgkmcnt(0)
	v_add_f32_e32 v16, v16, v17
	ds_write_b32 v190, v16 offset:640
.LBB0_824:
	s_or_b64 exec, exec, s[6:7]
	s_nop 0
	v_lshlrev_b32_e32 v18, 16, v68
	v_and_b32_e32 v19, 0xffff0000, v68
	v_lshlrev_b32_e32 v20, 16, v69
	v_and_b32_e32 v21, 0xffff0000, v69
	v_pk_add_f32 v[14:15], v[14:15], v[20:21]
	v_pk_add_f32 v[12:13], v[12:13], v[18:19]
	v_lshlrev_b32_e32 v18, 16, v70
	v_and_b32_e32 v19, 0xffff0000, v70
	v_lshlrev_b32_e32 v20, 16, v71
	v_and_b32_e32 v21, 0xffff0000, v71
	v_pk_add_f32 v[20:21], v[10:11], v[20:21]
	v_pk_add_f32 v[10:11], v[8:9], v[18:19]
	v_mul_f32_e32 v8, v13, v13
	v_mul_f32_e32 v9, v15, v15
	v_fmac_f32_e32 v8, v12, v12
	v_fmac_f32_e32 v9, v14, v14
	v_add_f32_e32 v8, v8, v9
	v_mul_f32_e32 v9, v11, v11
	v_mul_f32_e32 v18, v21, v21
	v_fmac_f32_e32 v9, v10, v10
	v_fmac_f32_e32 v18, v20, v20
	v_add_f32_e32 v9, v9, v18
	v_add_f32_e32 v18, v8, v9
	v_cvt_pk_bf16_f32 v8, v12, v13
	v_cvt_pk_bf16_f32 v9, v14, v15
	s_nop 0
	v_lshlrev_b32_e32 v12, 16, v64
	v_and_b32_e32 v13, 0xffff0000, v64
	v_lshlrev_b32_e32 v14, 16, v65
	v_and_b32_e32 v15, 0xffff0000, v65
	v_pk_add_f32 v[6:7], v[6:7], v[14:15]
	v_pk_add_f32 v[4:5], v[4:5], v[12:13]
	v_lshlrev_b32_e32 v12, 16, v66
	v_and_b32_e32 v13, 0xffff0000, v66
	v_lshlrev_b32_e32 v14, 16, v67
	v_and_b32_e32 v15, 0xffff0000, v67
	v_pk_add_f32 v[12:13], v[0:1], v[12:13]
	v_mul_f32_e32 v0, v5, v5
	v_mul_f32_e32 v1, v7, v7
	v_pk_add_f32 v[14:15], v[2:3], v[14:15]
	v_fmac_f32_e32 v0, v4, v4
	v_fmac_f32_e32 v1, v6, v6
	v_add_f32_e32 v0, v0, v1
	v_mul_f32_e32 v1, v13, v13
	v_mul_f32_e32 v2, v15, v15
	v_fmac_f32_e32 v1, v12, v12
	v_fmac_f32_e32 v2, v14, v14
	v_add_f32_e32 v1, v1, v2
	v_add_f32_e32 v0, v0, v1
	v_add_f32_e32 v0, v18, v0
	ds_bpermute_b32 v1, v198, v0
	s_waitcnt lgkmcnt(1)
	v_lshl_add_u64 v[16:17], s[84:85], 0, v[92:93]
	v_lshl_add_u64 v[16:17], v[168:169], 1, v[16:17]
	v_cvt_pk_bf16_f32 v10, v10, v11
	v_cvt_pk_bf16_f32 v11, v20, v21
	s_waitcnt lgkmcnt(0)
	v_add_f32_e32 v0, v0, v1
	ds_bpermute_b32 v1, v197, v0
	v_cvt_pk_bf16_f32 v2, v4, v5
	v_cvt_pk_bf16_f32 v3, v6, v7
	v_cvt_pk_bf16_f32 v4, v12, v13
	v_cvt_pk_bf16_f32 v5, v14, v15
	global_store_dwordx4 v[16:17], v[8:11], off
	global_store_dwordx4 v[16:17], v[2:5], off offset:256
	s_and_saveexec_b64 s[6:7], s[38:39]
	s_cbranch_execz .LBB0_826
	s_waitcnt lgkmcnt(0)
	v_add_f32_e32 v0, v0, v1
	ds_write_b32 v190, v0 offset:704
